# stacked: lru conv-window loads batched + hgrn gate load hoisted + gmlp v groups loaded together + lru_fix carry loads issued together
# baseline (speedup 1.0000x reference)
; __device__ __forceinline__ int opaque_bid() { int t = blockIdx.x; asm volatile("" : "+s"(t)); return t; }
; __device__ __forceinline__ int opaque_gd() { int t = gridDim.x; asm volatile("" : "+s"(t)); return t; }
; __device__ __forceinline__ int opaque_tid() { int t = threadIdx.x; asm volatile("" : "+v"(t)); return t; }
; __device__ __forceinline__ Params fetchP(const LAS Params* lp0) { unsigned la = (unsigned)(unsigned long long)lp0; asm volatile("" : "+v"(la)); const LAS Params* lp = (const LAS Params*)la; Params q; PFIELDS(PFETCH) q.ph_lo = 0; q.ph_hi = 0; return q; }
; __device__ __forceinline__ void lru_fix_item(const Params& p, int l, int item) {
;     const int tid = opaque_tid(), wid = tid >> 6, lane = tid & 63;
;     const int b = item >> 6, h = (item >> 4) & 3, seg = item & 15;
;     const int t0 = seg * 128 + wid * 16; const size_t Tb = (size_t)b * SEQ;
;     const int ch = h * 64 + lane;
;     const float* sc = (const float*)p.hbuf + ((((size_t)b * 4 + h) * 16 + seg) * 8 + wid) * 2048 + lane * 16;
;     f32x4 hv[4], av[4]; unsigned gr[16];
; #pragma unroll
;     for (int q = 0; q < 4; ++q) { hv[q] = *(const f32x4*)(sc + q * 4); av[q] = *(const f32x4*)(sc + 1024 + q * 4); }
; #pragma unroll
;     for (int i = 0; i < 16; ++i) gr[i] = p.z[(Tb + t0 + i) * ZLD + 2560 + ch];
; __device__ __forceinline__ void run_phase(const LAS Params* lp, int ph, LAS unsigned char* lds) {
;     ...
;     case 1: for (int it = opaque_bid(); it < 1280; it += opaque_gd()) { const Params p = fetchP(lp); const int jx = (it & ~255) + (it & 7) * 32 + ((it & 255) >> 3);
;             if (it < 256) hgrn_item(p, l, jx, 0, lds); else if (it < 768) attn_item(p, l, jx - 256, lds); else lru_item(p, l, jx - 768, lds); } break;
;     case 2: for (int it = opaque_bid(); it < 1280; it += opaque_gd()) { const Params p = fetchP(lp); const int jx = (it & ~255) + (it & 7) * 32 + ((it & 255) >> 3);
;             if (it < 256) hgrn_item(p, l, jx, 1, lds); else if (it < 768) gmlp_item(p, l, jx - 256, lds); else lru_fix_item(p, l, jx - 768); } break;
.LBB0_307:
	v_mov_b32_e32 v0, s84
	ds_read2_b64 v[4:7], v0 offset0:8 offset1:9
	ds_read2_b64 v[8:11], v0 offset0:29 offset1:30
	s_lshl_b32 s7, s72, 5
	s_and_b32 s6, s72, 0xffffff00
	s_and_b32 s7, s7, 0xe0
	s_waitcnt lgkmcnt(0)
	v_readfirstlane_b32 s2, v4
	v_readfirstlane_b32 s20, v5
	v_readfirstlane_b32 s23, v6
	v_readfirstlane_b32 s36, v7
	ds_read2_b64 v[4:7], v0 offset0:11 offset1:31
	s_or_b32 s21, s7, s6
	v_readfirstlane_b32 s34, v8
	v_readfirstlane_b32 s35, v9
	v_readfirstlane_b32 s9, v10
	s_waitcnt lgkmcnt(0)
	v_readfirstlane_b32 s0, v4
	v_readfirstlane_b32 s14, v5
	v_readfirstlane_b32 s30, v6
	v_readfirstlane_b32 s31, v7
	ds_read2_b64 v[4:7], v0 offset0:33 offset1:37
	v_readfirstlane_b32 s33, v11
	s_mov_b64 s[6:7], -1
	s_cmpk_gt_i32 s72, 0xff
	s_waitcnt lgkmcnt(0)
	v_readfirstlane_b32 s4, v4
	v_readfirstlane_b32 s5, v5
	v_readfirstlane_b32 s18, v6
	v_readfirstlane_b32 s19, v7
	ds_read2_b64 v[4:7], v0 offset0:39 offset1:40
	ds_read_b64 v[0:1], v0 offset:328
	s_waitcnt lgkmcnt(1)
	v_readfirstlane_b32 s15, v4
	v_readfirstlane_b32 s17, v5
	v_readfirstlane_b32 s10, v6
	v_readfirstlane_b32 s11, v7
	s_waitcnt lgkmcnt(0)
	v_readfirstlane_b32 s12, v0
	v_readfirstlane_b32 s13, v1
	s_cbranch_scc0 .LBB0_326
	s_bfe_u32 s6, s72, 0x50003
	s_or_b32 s16, s21, s6
	s_cmpk_gt_u32 s72, 0x2ff
	s_mov_b64 s[6:7], -1
	s_cbranch_scc0 .LBB0_319
	s_add_i32 s6, s21, 0xfffffd00
	s_ashr_i32 s38, s6, 6
	s_bfe_u32 s37, s16, 0x20004
	s_ashr_i32 s39, s38, 31
	s_lshl_b64 s[6:7], s[38:39], 6
	s_lshl_b32 s8, s37, 4
	s_bfe_u32 s22, s72, 0x40003
	s_or_b32 s8, s6, s8
	s_or_b32 s6, s8, s22
	v_mov_b32_e32 v1, v202
	s_lshl_b64 s[40:41], s[6:7], 16
	s_add_u32 s40, s9, s40
	v_ashrrev_i32_e32 v0, 6, v1
	v_and_b32_e32 v36, 63, v1
	v_ashrrev_i32_e32 v1, 31, v0
	s_addc_u32 s41, s33, s41
	s_lshl_b32 s6, s22, 7
	v_lshlrev_b64 v[4:5], 13, v[0:1]
	v_lshl_add_u32 v0, v0, 4, s6
	s_lshl_b64 s[38:39], s[38:39], 11
	v_ashrrev_i32_e32 v1, 31, v0
	v_lshl_add_u64 v[4:5], s[40:41], 0, v[4:5]
	v_lshlrev_b32_e32 v6, 6, v36
	v_mov_b32_e32 v7, v2
	v_lshl_add_u64 v[38:39], s[38:39], 0, v[0:1]
	v_mov_b64_e32 v[0:1], s[34:35]
	s_movk_i32 s6, 0x1600
	v_lshl_add_u64 v[8:9], v[4:5], 0, v[6:7]
	s_mov_b64 s[40:41], 0x1000
	v_lshl_or_b32 v3, s37, 6, v36
	v_mad_u64_u32 v[40:41], s[38:39], v38, s6, v[0:1]
	v_lshl_add_u64 v[24:25], v[8:9], 0, s[40:41]
	global_load_dwordx4 v[4:7], v[8:9], off offset:48
	global_load_dwordx4 v[12:15], v[8:9], off offset:32
	global_load_dwordx4 v[20:23], v[8:9], off offset:16
	global_load_dwordx4 v[28:31], v[8:9], off
	v_add_co_u32_e32 v8, vcc, s80, v8
	v_mad_i32_i24 v41, v39, s6, v41
	v_lshlrev_b32_e32 v0, 1, v3
	v_mov_b32_e32 v1, v2
	v_addc_co_u32_e32 v9, vcc, 0, v9, vcc
	v_lshl_add_u64 v[40:41], v[40:41], 0, v[0:1]
	v_add_co_u32_e32 v42, vcc, s80, v40
	global_load_dwordx4 v[32:35], v[8:9], off
	s_nop 0
	global_load_dwordx4 v[8:11], v[24:25], off offset:48
	global_load_dwordx4 v[16:19], v[24:25], off offset:32
	s_nop 0
	global_load_dwordx4 v[24:27], v[24:25], off offset:16
	v_addc_co_u32_e32 v43, vcc, 0, v41, vcc
	global_load_ushort v1, v[42:43], off offset:1024
	v_add_co_u32_e32 v42, vcc, s81, v40
	s_movk_i32 s6, 0x4000
	s_nop 0
	v_addc_co_u32_e32 v43, vcc, 0, v41, vcc
	global_load_ushort v55, v[42:43], off offset:2560
	v_add_co_u32_e32 v42, vcc, s6, v40
	s_movk_i32 s6, 0x5000
	s_nop 0
	v_addc_co_u32_e32 v43, vcc, 0, v41, vcc
	global_load_ushort v54, v[42:43], off
	v_add_co_u32_e32 v42, vcc, s6, v40
	s_movk_i32 s6, 0x6000
	s_nop 0
	v_addc_co_u32_e32 v43, vcc, 0, v41, vcc
	global_load_ushort v53, v[42:43], off offset:1536
	v_add_co_u32_e32 v42, vcc, s6, v40
	s_mov_b32 s6, 0x8000
	s_nop 0
	v_addc_co_u32_e32 v43, vcc, 0, v41, vcc
	global_load_ushort v52, v[42:43], off offset:3072
	v_add_co_u32_e32 v42, vcc, s6, v40
	s_mov_b32 s6, 0x9000
	s_nop 0
	v_addc_co_u32_e32 v43, vcc, 0, v41, vcc
	global_load_ushort v51, v[42:43], off offset:512
	v_add_co_u32_e32 v42, vcc, s6, v40
	s_mov_b32 s6, 0xa000
	s_nop 0
	v_addc_co_u32_e32 v43, vcc, 0, v41, vcc
	global_load_ushort v50, v[42:43], off offset:2048
	v_add_co_u32_e32 v42, vcc, s6, v40
	s_mov_b32 s6, 0xc000
	s_nop 0
	v_addc_co_u32_e32 v43, vcc, 0, v41, vcc
	global_load_ushort v49, v[42:43], off offset:3584
	v_add_co_u32_e32 v42, vcc, s6, v40
	s_mov_b32 s6, 0xd000
	s_nop 0
	v_addc_co_u32_e32 v43, vcc, 0, v41, vcc
	global_load_ushort v48, v[42:43], off offset:1024
	v_add_co_u32_e32 v42, vcc, s6, v40
	s_mov_b32 s6, 0xf000
	s_nop 0
	v_addc_co_u32_e32 v43, vcc, 0, v41, vcc
	global_load_ushort v47, v[42:43], off offset:2560
	v_add_co_u32_e32 v42, vcc, s6, v40
	s_mov_b32 s6, 0x10000
	s_nop 0
	v_addc_co_u32_e32 v43, vcc, 0, v41, vcc
	global_load_ushort v46, v[42:43], off
	v_add_co_u32_e32 v42, vcc, s6, v40
	s_cmp_eq_u32 s22, 0
	s_nop 0
	v_addc_co_u32_e32 v43, vcc, 0, v41, vcc
	global_load_ushort v45, v[42:43], off offset:1536
	v_add_co_u32_e32 v42, vcc, 0x11000, v40
	s_nop 1
	v_addc_co_u32_e32 v43, vcc, 0, v41, vcc
	global_load_ushort v44, v[42:43], off offset:3072
	v_add_co_u32_e32 v42, vcc, 0x13000, v40
	s_nop 1
	v_addc_co_u32_e32 v43, vcc, 0, v41, vcc
	v_add_co_u32_e32 v56, vcc, 0x14000, v40
	global_load_ushort v43, v[42:43], off offset:512
	s_nop 0
	v_addc_co_u32_e32 v57, vcc, 0, v41, vcc
	v_add_co_u32_e32 v40, vcc, 0x15000, v40
	global_load_ushort v42, v[56:57], off offset:2048
	s_nop 0
	v_addc_co_u32_e32 v41, vcc, 0, v41, vcc
	global_load_ushort v3, v[40:41], off offset:3584
	s_cbranch_scc1 .LBB0_314
; __device__ __forceinline__ void lru_fix_item(const Params& p, int l, int item) {
;     ...
;     const float* car = p.lru_carry + (((size_t)b * 4 + h) * 16) * 128;
;     float Hin = 0.f;
; #pragma unroll 4
;     for (int s = 0; s < seg; ++s) { const float as = car[s * 128 + lane * 2], hs = car[s * 128 + lane * 2 + 1]; Hin = as * Hin + hs; }
	s_mov_b32 s9, s7
	s_lshl_b64 s[6:7], s[8:9], 9
	s_add_u32 s6, s15, s6
	s_addc_u32 s7, s17, s7
	v_lshlrev_b32_e32 v56, 3, v36
	s_mov_b32 s38, 0x16000
	s_add_u32 s8, s6, 0x1000
	s_addc_u32 s9, s7, 0
	s_cmp_le_u32 s22, 0
	s_cbranch_scc1 .Llrufix_issued
	global_load_dwordx2 v[62:63], v56, s[6:7] offset:0
	s_cmp_le_u32 s22, 1
	s_cbranch_scc1 .Llrufix_issued
	global_load_dwordx2 v[64:65], v56, s[6:7] offset:512
	s_cmp_le_u32 s22, 2
	s_cbranch_scc1 .Llrufix_issued
	global_load_dwordx2 v[66:67], v56, s[6:7] offset:1024
	s_cmp_le_u32 s22, 3
	s_cbranch_scc1 .Llrufix_issued
	global_load_dwordx2 v[68:69], v56, s[6:7] offset:1536
	s_cmp_le_u32 s22, 4
	s_cbranch_scc1 .Llrufix_issued
	global_load_dwordx2 v[70:71], v56, s[6:7] offset:2048
	s_cmp_le_u32 s22, 5
	s_cbranch_scc1 .Llrufix_issued
	global_load_dwordx2 v[72:73], v56, s[6:7] offset:2560
	s_cmp_le_u32 s22, 6
	s_cbranch_scc1 .Llrufix_issued
	global_load_dwordx2 v[74:75], v56, s[6:7] offset:3072
	s_cmp_le_u32 s22, 7
	s_cbranch_scc1 .Llrufix_issued
	global_load_dwordx2 v[76:77], v56, s[6:7] offset:3584
	s_cmp_le_u32 s22, 8
	s_cbranch_scc1 .Llrufix_issued
	global_load_dwordx2 v[78:79], v56, s[8:9] offset:0
	s_cmp_le_u32 s22, 9
	s_cbranch_scc1 .Llrufix_issued
	global_load_dwordx2 v[80:81], v56, s[8:9] offset:512
	s_cmp_le_u32 s22, 10
	s_cbranch_scc1 .Llrufix_issued
	global_load_dwordx2 v[82:83], v56, s[8:9] offset:1024
	s_cmp_le_u32 s22, 11
	s_cbranch_scc1 .Llrufix_issued
	global_load_dwordx2 v[84:85], v56, s[8:9] offset:1536
	s_cmp_le_u32 s22, 12
	s_cbranch_scc1 .Llrufix_issued
	global_load_dwordx2 v[86:87], v56, s[8:9] offset:2048
	s_cmp_le_u32 s22, 13
	s_cbranch_scc1 .Llrufix_issued
	global_load_dwordx2 v[88:89], v56, s[8:9] offset:2560
	s_cmp_le_u32 s22, 14
	s_cbranch_scc1 .Llrufix_issued
	global_load_dwordx2 v[90:91], v56, s[8:9] offset:3072
